# grid barrier: non-leader workgroups poll the cross-XCD release generation directly instead of the per-XCD word (one hop less per barrier)
# speedup vs baseline: 1.0040x; 1.0040x over previous
; __device__ __forceinline__ unsigned xb_ld(unsigned* p)              { return __hip_atomic_load(p, __ATOMIC_RELAXED, __HIP_MEMORY_SCOPE_AGENT); }
; __device__ __forceinline__ unsigned xb_add(unsigned* p, unsigned v) { return __hip_atomic_fetch_add(p, v, __ATOMIC_RELAXED, __HIP_MEMORY_SCOPE_AGENT); }
; #define XB_SPIN(cond, bar) do { unsigned _sp = 0; while (cond) { __builtin_amdgcn_s_sleep(1); \
;     if ((++_sp & 255u) == 0u) { if (xb_ld(&(bar)[XB_TMO])) break; if (_sp > XB_SPIN_CAP) { atomicAdd(&(bar)[XB_TMO], 1u); break; } } } } while (0)
; __device__ __forceinline__ void xcd_barrier(const XcdBarrier& b, int tid) {
;     ...
;         const unsigned old = xb_add(&bar[XB_XSUB(bx_)], 1u);
;         const unsigned gen = old / nloc;
;         if (old + 1u == (gen + 1u) * nloc) {
;             __builtin_amdgcn_fence(__ATOMIC_RELEASE, "agent");
;             asm volatile("s_waitcnt vmcnt(0)" ::: "memory");
;             const unsigned og = xb_add(&bar[XB_TOP], 1u);
;             const unsigned tg = og / nx;
;             if (og + 1u == (tg + 1u) * nx) xb_add(&bar[XB_TOPGEN], 1u);
;             else XB_SPIN(xb_ld(&bar[XB_TOPGEN]) == tg, bar);
;             __builtin_amdgcn_fence(__ATOMIC_ACQUIRE, "agent");
;             xb_add(&bar[XB_XGEN(bx_)], 1u);
;             asm volatile("s_waitcnt vmcnt(0)" ::: "memory");
;         } else {
;             XB_SPIN(xb_ld(&bar[XB_XGEN(bx_)]) == gen, bar);
;             __builtin_amdgcn_fence(__ATOMIC_ACQUIRE, "agent");
;             asm volatile("s_waitcnt vmcnt(0)" ::: "memory");
;         }
.LBB0_90:
	s_lshl_b32 s24, s33, 6
	s_add_i32 s4, s24, 0x500
	s_mov_b32 s5, 0
	s_lshl_b64 s[0:1], s[4:5], 2
	s_add_u32 s0, s34, s0
	s_addc_u32 s1, s35, s1
	v_mov_b32_e32 v1, 1
	v_mov_b64_e32 v[4:5], s[0:1]
	flat_atomic_add v1, v[4:5], v1 sc0
	v_cvt_f32_u32_e32 v3, v2
	v_sub_u32_e32 v4, 0, v2
	v_rcp_iflag_f32_e32 v3, v3
	s_nop 0
	v_mul_f32_e32 v3, 0x4f7ffffe, v3
	v_cvt_u32_f32_e32 v3, v3
	v_mul_lo_u32 v4, v4, v3
	v_mul_hi_u32 v4, v3, v4
	v_add_u32_e32 v3, v3, v4
	s_waitcnt vmcnt(0) lgkmcnt(0)
	v_mul_hi_u32 v3, v1, v3
	v_mul_lo_u32 v5, v3, v2
	v_add_u32_e32 v4, 1, v1
	v_sub_u32_e32 v1, v1, v5
	v_add_u32_e32 v6, 1, v3
	v_cmp_ge_u32_e32 vcc, v1, v2
	v_sub_u32_e32 v5, v1, v2
	s_nop 0
	v_cndmask_b32_e32 v3, v3, v6, vcc
	v_cndmask_b32_e32 v1, v1, v5, vcc
	v_add_u32_e32 v5, 1, v3
	v_cmp_ge_u32_e32 vcc, v1, v2
	s_nop 1
	v_cndmask_b32_e32 v1, v3, v5, vcc
	v_mad_u64_u32 v[2:3], s[0:1], v2, v1, v[2:3]
	v_cmp_ne_u32_e32 vcc, v4, v2
	s_and_saveexec_b64 s[0:1], vcc
	s_xor_b64 s[0:1], exec, s[0:1]
	s_cbranch_execz .LBB0_103
	s_add_i32 s4, s24, 0x900
	s_lshl_b64 s[4:5], s[4:5], 2
	s_add_u32 s6, s34, 0x3500
	s_addc_u32 s7, s35, 0
	v_mov_b64_e32 v[2:3], s[6:7]
	global_load_dword v0, v[2:3], off sc1
	s_waitcnt vmcnt(0) lgkmcnt(0)
	v_cmp_eq_u32_e32 vcc, v0, v1
	s_and_saveexec_b64 s[4:5], vcc
	s_cbranch_execz .LBB0_102
	s_mov_b32 s22, 1
	s_mov_b64 s[8:9], 0
	s_branch .LBB0_94

; __device__ __forceinline__ unsigned xb_ld(unsigned* p)              { return __hip_atomic_load(p, __ATOMIC_RELAXED, __HIP_MEMORY_SCOPE_AGENT); }
; __device__ __forceinline__ unsigned xb_add(unsigned* p, unsigned v) { return __hip_atomic_fetch_add(p, v, __ATOMIC_RELAXED, __HIP_MEMORY_SCOPE_AGENT); }
; #define XB_SPIN(cond, bar) do { unsigned _sp = 0; while (cond) { __builtin_amdgcn_s_sleep(1); \
;     if ((++_sp & 255u) == 0u) { if (xb_ld(&(bar)[XB_TMO])) break; if (_sp > XB_SPIN_CAP) { atomicAdd(&(bar)[XB_TMO], 1u); break; } } } } while (0)
; __device__ __forceinline__ void xcd_barrier(const XcdBarrier& b, int tid) {
;     ...
;         const unsigned old = xb_add(&bar[XB_XSUB(bx_)], 1u);
;         const unsigned gen = old / nloc;
;         if (old + 1u == (gen + 1u) * nloc) {
;             __builtin_amdgcn_fence(__ATOMIC_RELEASE, "agent");
;             asm volatile("s_waitcnt vmcnt(0)" ::: "memory");
;             const unsigned og = xb_add(&bar[XB_TOP], 1u);
;             const unsigned tg = og / nx;
;             if (og + 1u == (tg + 1u) * nx) xb_add(&bar[XB_TOPGEN], 1u);
;             else XB_SPIN(xb_ld(&bar[XB_TOPGEN]) == tg, bar);
;             __builtin_amdgcn_fence(__ATOMIC_ACQUIRE, "agent");
;             xb_add(&bar[XB_XGEN(bx_)], 1u);
;             asm volatile("s_waitcnt vmcnt(0)" ::: "memory");
;         } else {
;             XB_SPIN(xb_ld(&bar[XB_XGEN(bx_)]) == gen, bar);
;             __builtin_amdgcn_fence(__ATOMIC_ACQUIRE, "agent");
;             asm volatile("s_waitcnt vmcnt(0)" ::: "memory");
;         }
.LBB0_151:
	s_lshl_b32 s22, s33, 6
	s_add_i32 s4, s22, 0x500
	s_mov_b32 s5, 0
	s_lshl_b64 s[0:1], s[4:5], 2
	s_add_u32 s0, s34, s0
	s_addc_u32 s1, s35, s1
	v_mov_b32_e32 v1, 1
	v_mov_b64_e32 v[4:5], s[0:1]
	flat_atomic_add v1, v[4:5], v1 sc0
	v_cvt_f32_u32_e32 v3, v2
	v_sub_u32_e32 v4, 0, v2
	v_rcp_iflag_f32_e32 v3, v3
	s_nop 0
	v_mul_f32_e32 v3, 0x4f7ffffe, v3
	v_cvt_u32_f32_e32 v3, v3
	v_mul_lo_u32 v4, v4, v3
	v_mul_hi_u32 v4, v3, v4
	v_add_u32_e32 v3, v3, v4
	s_waitcnt vmcnt(0) lgkmcnt(0)
	v_mul_hi_u32 v3, v1, v3
	v_mul_lo_u32 v5, v3, v2
	v_add_u32_e32 v4, 1, v1
	v_sub_u32_e32 v1, v1, v5
	v_add_u32_e32 v6, 1, v3
	v_cmp_ge_u32_e32 vcc, v1, v2
	v_sub_u32_e32 v5, v1, v2
	s_nop 0
	v_cndmask_b32_e32 v3, v3, v6, vcc
	v_cndmask_b32_e32 v1, v1, v5, vcc
	v_add_u32_e32 v5, 1, v3
	v_cmp_ge_u32_e32 vcc, v1, v2
	s_nop 1
	v_cndmask_b32_e32 v1, v3, v5, vcc
	v_mad_u64_u32 v[2:3], s[0:1], v2, v1, v[2:3]
	v_cmp_ne_u32_e32 vcc, v4, v2
	s_and_saveexec_b64 s[0:1], vcc
	s_xor_b64 s[0:1], exec, s[0:1]
	s_cbranch_execz .LBB0_164
	s_add_i32 s4, s22, 0x900
	s_lshl_b64 s[4:5], s[4:5], 2
	s_add_u32 s6, s34, 0x3500
	s_addc_u32 s7, s35, 0
	v_mov_b64_e32 v[2:3], s[6:7]
	global_load_dword v0, v[2:3], off sc1
	s_waitcnt vmcnt(0) lgkmcnt(0)
	v_cmp_eq_u32_e32 vcc, v0, v1
	s_and_saveexec_b64 s[4:5], vcc
	s_cbranch_execz .LBB0_163
	s_mov_b32 s23, 1
	s_mov_b64 s[8:9], 0
	s_branch .LBB0_155

; __device__ __forceinline__ unsigned xb_ld(unsigned* p)              { return __hip_atomic_load(p, __ATOMIC_RELAXED, __HIP_MEMORY_SCOPE_AGENT); }
; __device__ __forceinline__ unsigned xb_add(unsigned* p, unsigned v) { return __hip_atomic_fetch_add(p, v, __ATOMIC_RELAXED, __HIP_MEMORY_SCOPE_AGENT); }
; #define XB_SPIN(cond, bar) do { unsigned _sp = 0; while (cond) { __builtin_amdgcn_s_sleep(1); \
;     if ((++_sp & 255u) == 0u) { if (xb_ld(&(bar)[XB_TMO])) break; if (_sp > XB_SPIN_CAP) { atomicAdd(&(bar)[XB_TMO], 1u); break; } } } } while (0)
; __device__ __forceinline__ void xcd_barrier(const XcdBarrier& b, int tid) {
;     ...
;         const unsigned old = xb_add(&bar[XB_XSUB(bx_)], 1u);
;         const unsigned gen = old / nloc;
;         if (old + 1u == (gen + 1u) * nloc) {
;             __builtin_amdgcn_fence(__ATOMIC_RELEASE, "agent");
;             asm volatile("s_waitcnt vmcnt(0)" ::: "memory");
;             const unsigned og = xb_add(&bar[XB_TOP], 1u);
;             const unsigned tg = og / nx;
;             if (og + 1u == (tg + 1u) * nx) xb_add(&bar[XB_TOPGEN], 1u);
;             else XB_SPIN(xb_ld(&bar[XB_TOPGEN]) == tg, bar);
;             __builtin_amdgcn_fence(__ATOMIC_ACQUIRE, "agent");
;             xb_add(&bar[XB_XGEN(bx_)], 1u);
;             asm volatile("s_waitcnt vmcnt(0)" ::: "memory");
;         } else {
;             XB_SPIN(xb_ld(&bar[XB_XGEN(bx_)]) == gen, bar);
;             __builtin_amdgcn_fence(__ATOMIC_ACQUIRE, "agent");
;             asm volatile("s_waitcnt vmcnt(0)" ::: "memory");
;         }
.LBB0_213:
	s_lshl_b32 s24, s36, 6
	s_add_i32 s64, s24, 0x500
	s_lshl_b64 s[0:1], s[64:65], 2
	s_add_u32 s0, s34, s0
	s_addc_u32 s1, s35, s1
	v_mov_b64_e32 v[4:5], s[0:1]
	v_mov_b32_e32 v1, 1
	flat_atomic_add v3, v[4:5], v1 sc0
	v_cvt_f32_u32_e32 v1, v2
	v_sub_u32_e32 v4, 0, v2
	v_rcp_iflag_f32_e32 v1, v1
	s_nop 0
	v_mul_f32_e32 v1, 0x4f7ffffe, v1
	v_cvt_u32_f32_e32 v1, v1
	v_mul_lo_u32 v4, v4, v1
	v_mul_hi_u32 v4, v1, v4
	v_add_u32_e32 v1, v1, v4
	s_waitcnt vmcnt(0) lgkmcnt(0)
	v_mul_hi_u32 v1, v3, v1
	v_mul_lo_u32 v4, v1, v2
	v_sub_u32_e32 v4, v3, v4
	v_cmp_ge_u32_e32 vcc, v4, v2
	v_add_u32_e32 v5, 1, v1
	s_nop 0
	v_cndmask_b32_e32 v1, v1, v5, vcc
	v_sub_u32_e32 v5, v4, v2
	v_cndmask_b32_e32 v4, v4, v5, vcc
	v_cmp_ge_u32_e32 vcc, v4, v2
	v_add_u32_e32 v4, 1, v1
	s_nop 0
	v_cndmask_b32_e32 v1, v1, v4, vcc
	v_add_u32_e32 v4, 1, v3
	v_mad_u64_u32 v[2:3], s[0:1], v2, v1, v[2:3]
	v_cmp_ne_u32_e32 vcc, v4, v2
	s_and_saveexec_b64 s[0:1], vcc
	s_xor_b64 s[0:1], exec, s[0:1]
	s_cbranch_execz .LBB0_226
	s_add_i32 s64, s24, 0x900
	s_lshl_b64 s[4:5], s[64:65], 2
	s_add_u32 s6, s34, 0x3500
	s_addc_u32 s7, s35, 0
	v_mov_b64_e32 v[2:3], s[6:7]
	global_load_dword v0, v[2:3], off sc1
	s_waitcnt vmcnt(0) lgkmcnt(0)
	v_cmp_eq_u32_e32 vcc, v0, v1
	s_and_saveexec_b64 s[4:5], vcc
	s_cbranch_execz .LBB0_225
	s_mov_b32 s22, 1
	s_mov_b64 s[8:9], 0
	s_branch .LBB0_217

; __device__ __forceinline__ unsigned xb_ld(unsigned* p)              { return __hip_atomic_load(p, __ATOMIC_RELAXED, __HIP_MEMORY_SCOPE_AGENT); }
; __device__ __forceinline__ unsigned xb_add(unsigned* p, unsigned v) { return __hip_atomic_fetch_add(p, v, __ATOMIC_RELAXED, __HIP_MEMORY_SCOPE_AGENT); }
; #define XB_SPIN(cond, bar) do { unsigned _sp = 0; while (cond) { __builtin_amdgcn_s_sleep(1); \
;     if ((++_sp & 255u) == 0u) { if (xb_ld(&(bar)[XB_TMO])) break; if (_sp > XB_SPIN_CAP) { atomicAdd(&(bar)[XB_TMO], 1u); break; } } } } while (0)
; __device__ __forceinline__ void xcd_barrier(const XcdBarrier& b, int tid) {
;     ...
;         const unsigned old = xb_add(&bar[XB_XSUB(bx_)], 1u);
;         const unsigned gen = old / nloc;
;         if (old + 1u == (gen + 1u) * nloc) {
;             __builtin_amdgcn_fence(__ATOMIC_RELEASE, "agent");
;             asm volatile("s_waitcnt vmcnt(0)" ::: "memory");
;             const unsigned og = xb_add(&bar[XB_TOP], 1u);
;             const unsigned tg = og / nx;
;             if (og + 1u == (tg + 1u) * nx) xb_add(&bar[XB_TOPGEN], 1u);
;             else XB_SPIN(xb_ld(&bar[XB_TOPGEN]) == tg, bar);
;             __builtin_amdgcn_fence(__ATOMIC_ACQUIRE, "agent");
;             xb_add(&bar[XB_XGEN(bx_)], 1u);
;             asm volatile("s_waitcnt vmcnt(0)" ::: "memory");
;         } else {
;             XB_SPIN(xb_ld(&bar[XB_XGEN(bx_)]) == gen, bar);
;             __builtin_amdgcn_fence(__ATOMIC_ACQUIRE, "agent");
;             asm volatile("s_waitcnt vmcnt(0)" ::: "memory");
;         }
.LBB0_772:
	s_lshl_b32 s0, s0, 6
	s_add_i32 s64, s0, 0x500
	s_lshl_b64 s[4:5], s[64:65], 2
	s_add_u32 s4, s36, s4
	s_addc_u32 s5, s37, s5
	v_mov_b64_e32 v[4:5], s[4:5]
	v_mov_b32_e32 v1, 1
	flat_atomic_add v3, v[4:5], v1 sc0
	v_cvt_f32_u32_e32 v1, v2
	v_sub_u32_e32 v4, 0, v2
	v_rcp_iflag_f32_e32 v1, v1
	s_nop 0
	v_mul_f32_e32 v1, 0x4f7ffffe, v1
	v_cvt_u32_f32_e32 v1, v1
	v_mul_lo_u32 v4, v4, v1
	v_mul_hi_u32 v4, v1, v4
	v_add_u32_e32 v1, v1, v4
	s_waitcnt vmcnt(0) lgkmcnt(0)
	v_mul_hi_u32 v1, v3, v1
	v_mul_lo_u32 v4, v1, v2
	v_sub_u32_e32 v4, v3, v4
	v_cmp_ge_u32_e32 vcc, v4, v2
	v_add_u32_e32 v5, 1, v1
	s_nop 0
	v_cndmask_b32_e32 v1, v1, v5, vcc
	v_sub_u32_e32 v5, v4, v2
	v_cndmask_b32_e32 v4, v4, v5, vcc
	v_cmp_ge_u32_e32 vcc, v4, v2
	v_add_u32_e32 v4, 1, v1
	s_nop 0
	v_cndmask_b32_e32 v1, v1, v4, vcc
	v_add_u32_e32 v4, 1, v3
	v_mad_u64_u32 v[2:3], s[4:5], v2, v1, v[2:3]
	v_cmp_ne_u32_e32 vcc, v4, v2
	s_and_saveexec_b64 s[4:5], vcc
	s_xor_b64 s[4:5], exec, s[4:5]
	s_cbranch_execz .LBB0_785
	s_add_i32 s64, s0, 0x900
	s_lshl_b64 s[6:7], s[64:65], 2
	s_add_u32 s8, s36, 0x3500
	s_addc_u32 s9, s37, 0
	v_mov_b64_e32 v[2:3], s[8:9]
	global_load_dword v0, v[2:3], off sc1
	s_waitcnt vmcnt(0) lgkmcnt(0)
	v_cmp_eq_u32_e32 vcc, v0, v1
	s_and_saveexec_b64 s[6:7], vcc
	s_cbranch_execz .LBB0_784
	s_mov_b32 s1, 1
	s_mov_b64 s[10:11], 0
	s_branch .LBB0_776

; __device__ __forceinline__ unsigned xb_ld(unsigned* p)              { return __hip_atomic_load(p, __ATOMIC_RELAXED, __HIP_MEMORY_SCOPE_AGENT); }
; __device__ __forceinline__ unsigned xb_add(unsigned* p, unsigned v) { return __hip_atomic_fetch_add(p, v, __ATOMIC_RELAXED, __HIP_MEMORY_SCOPE_AGENT); }
; #define XB_SPIN(cond, bar) do { unsigned _sp = 0; while (cond) { __builtin_amdgcn_s_sleep(1); \
;     if ((++_sp & 255u) == 0u) { if (xb_ld(&(bar)[XB_TMO])) break; if (_sp > XB_SPIN_CAP) { atomicAdd(&(bar)[XB_TMO], 1u); break; } } } } while (0)
; __device__ __forceinline__ void xcd_barrier(const XcdBarrier& b, int tid) {
;     ...
;         const unsigned old = xb_add(&bar[XB_XSUB(bx_)], 1u);
;         const unsigned gen = old / nloc;
;         if (old + 1u == (gen + 1u) * nloc) {
;             __builtin_amdgcn_fence(__ATOMIC_RELEASE, "agent");
;             asm volatile("s_waitcnt vmcnt(0)" ::: "memory");
;             const unsigned og = xb_add(&bar[XB_TOP], 1u);
;             const unsigned tg = og / nx;
;             if (og + 1u == (tg + 1u) * nx) xb_add(&bar[XB_TOPGEN], 1u);
;             else XB_SPIN(xb_ld(&bar[XB_TOPGEN]) == tg, bar);
;             __builtin_amdgcn_fence(__ATOMIC_ACQUIRE, "agent");
;             xb_add(&bar[XB_XGEN(bx_)], 1u);
;             asm volatile("s_waitcnt vmcnt(0)" ::: "memory");
;         } else {
;             XB_SPIN(xb_ld(&bar[XB_XGEN(bx_)]) == gen, bar);
;             __builtin_amdgcn_fence(__ATOMIC_ACQUIRE, "agent");
;             asm volatile("s_waitcnt vmcnt(0)" ::: "memory");
;         }
.LBB0_934:
	s_lshl_b32 s26, s36, 6
	s_add_i32 s64, s26, 0x500
	s_lshl_b64 s[4:5], s[64:65], 2
	s_add_u32 s4, s2, s4
	s_addc_u32 s5, s3, s5
	v_mov_b64_e32 v[4:5], s[4:5]
	v_mov_b32_e32 v1, 1
	flat_atomic_add v3, v[4:5], v1 sc0
	v_cvt_f32_u32_e32 v1, v2
	v_sub_u32_e32 v4, 0, v2
	v_rcp_iflag_f32_e32 v1, v1
	s_nop 0
	v_mul_f32_e32 v1, 0x4f7ffffe, v1
	v_cvt_u32_f32_e32 v1, v1
	v_mul_lo_u32 v4, v4, v1
	v_mul_hi_u32 v4, v1, v4
	v_add_u32_e32 v1, v1, v4
	s_waitcnt vmcnt(0) lgkmcnt(0)
	v_mul_hi_u32 v1, v3, v1
	v_mul_lo_u32 v4, v1, v2
	v_sub_u32_e32 v4, v3, v4
	v_cmp_ge_u32_e32 vcc, v4, v2
	v_add_u32_e32 v5, 1, v1
	s_nop 0
	v_cndmask_b32_e32 v1, v1, v5, vcc
	v_sub_u32_e32 v5, v4, v2
	v_cndmask_b32_e32 v4, v4, v5, vcc
	v_cmp_ge_u32_e32 vcc, v4, v2
	v_add_u32_e32 v4, 1, v1
	s_nop 0
	v_cndmask_b32_e32 v1, v1, v4, vcc
	v_add_u32_e32 v4, 1, v3
	v_mad_u64_u32 v[2:3], s[4:5], v2, v1, v[2:3]
	v_cmp_ne_u32_e32 vcc, v4, v2
	s_and_saveexec_b64 s[4:5], vcc
	s_xor_b64 s[4:5], exec, s[4:5]
	s_cbranch_execz .LBB0_947
	s_add_i32 s64, s26, 0x900
	s_lshl_b64 s[6:7], s[64:65], 2
	s_add_u32 s8, s2, 0x3500
	s_addc_u32 s9, s3, 0
	v_mov_b64_e32 v[2:3], s[8:9]
	global_load_dword v0, v[2:3], off sc1
	s_waitcnt vmcnt(0) lgkmcnt(0)
	v_cmp_eq_u32_e32 vcc, v0, v1
	s_and_saveexec_b64 s[6:7], vcc
	s_cbranch_execz .LBB0_946
	s_mov_b32 s24, 1
	s_mov_b64 s[10:11], 0
	s_branch .LBB0_938

; __device__ __forceinline__ unsigned xb_ld(unsigned* p)              { return __hip_atomic_load(p, __ATOMIC_RELAXED, __HIP_MEMORY_SCOPE_AGENT); }
; __device__ __forceinline__ unsigned xb_add(unsigned* p, unsigned v) { return __hip_atomic_fetch_add(p, v, __ATOMIC_RELAXED, __HIP_MEMORY_SCOPE_AGENT); }
; #define XB_SPIN(cond, bar) do { unsigned _sp = 0; while (cond) { __builtin_amdgcn_s_sleep(1); \
;     if ((++_sp & 255u) == 0u) { if (xb_ld(&(bar)[XB_TMO])) break; if (_sp > XB_SPIN_CAP) { atomicAdd(&(bar)[XB_TMO], 1u); break; } } } } while (0)
; __device__ __forceinline__ void xcd_barrier(const XcdBarrier& b, int tid) {
;     ...
;         const unsigned old = xb_add(&bar[XB_XSUB(bx_)], 1u);
;         const unsigned gen = old / nloc;
;         if (old + 1u == (gen + 1u) * nloc) {
;             __builtin_amdgcn_fence(__ATOMIC_RELEASE, "agent");
;             asm volatile("s_waitcnt vmcnt(0)" ::: "memory");
;             const unsigned og = xb_add(&bar[XB_TOP], 1u);
;             const unsigned tg = og / nx;
;             if (og + 1u == (tg + 1u) * nx) xb_add(&bar[XB_TOPGEN], 1u);
;             else XB_SPIN(xb_ld(&bar[XB_TOPGEN]) == tg, bar);
;             __builtin_amdgcn_fence(__ATOMIC_ACQUIRE, "agent");
;             xb_add(&bar[XB_XGEN(bx_)], 1u);
;             asm volatile("s_waitcnt vmcnt(0)" ::: "memory");
;         } else {
;             XB_SPIN(xb_ld(&bar[XB_XGEN(bx_)]) == gen, bar);
;             __builtin_amdgcn_fence(__ATOMIC_ACQUIRE, "agent");
;             asm volatile("s_waitcnt vmcnt(0)" ::: "memory");
;         }
.LBB0_1031:
	s_lshl_b32 s28, s50, 6
	s_add_i32 s64, s28, 0x500
	s_lshl_b64 s[6:7], s[64:65], 2
	s_add_u32 s6, s2, s6
	s_addc_u32 s7, s3, s7
	v_mov_b64_e32 v[4:5], s[6:7]
	v_mov_b32_e32 v1, 1
	flat_atomic_add v3, v[4:5], v1 sc0
	v_cvt_f32_u32_e32 v1, v2
	v_sub_u32_e32 v4, 0, v2
	v_rcp_iflag_f32_e32 v1, v1
	s_nop 0
	v_mul_f32_e32 v1, 0x4f7ffffe, v1
	v_cvt_u32_f32_e32 v1, v1
	v_mul_lo_u32 v4, v4, v1
	v_mul_hi_u32 v4, v1, v4
	v_add_u32_e32 v1, v1, v4
	s_waitcnt vmcnt(0) lgkmcnt(0)
	v_mul_hi_u32 v1, v3, v1
	v_mul_lo_u32 v4, v1, v2
	v_sub_u32_e32 v4, v3, v4
	v_cmp_ge_u32_e32 vcc, v4, v2
	v_add_u32_e32 v5, 1, v1
	s_nop 0
	v_cndmask_b32_e32 v1, v1, v5, vcc
	v_sub_u32_e32 v5, v4, v2
	v_cndmask_b32_e32 v4, v4, v5, vcc
	v_cmp_ge_u32_e32 vcc, v4, v2
	v_add_u32_e32 v4, 1, v1
	s_nop 0
	v_cndmask_b32_e32 v1, v1, v4, vcc
	v_add_u32_e32 v4, 1, v3
	v_mad_u64_u32 v[2:3], s[6:7], v2, v1, v[2:3]
	v_cmp_ne_u32_e32 vcc, v4, v2
	s_and_saveexec_b64 s[6:7], vcc
	s_xor_b64 s[6:7], exec, s[6:7]
	s_cbranch_execz .LBB0_1044
	s_add_i32 s64, s28, 0x900
	s_lshl_b64 s[8:9], s[64:65], 2
	s_add_u32 s10, s2, 0x3500
	s_addc_u32 s11, s3, 0
	v_mov_b64_e32 v[2:3], s[10:11]
	global_load_dword v0, v[2:3], off sc1
	s_waitcnt vmcnt(0) lgkmcnt(0)
	v_cmp_eq_u32_e32 vcc, v0, v1
	s_and_saveexec_b64 s[8:9], vcc
	s_cbranch_execz .LBB0_1043
	s_mov_b32 s26, 1
	s_mov_b64 s[12:13], 0
	s_branch .LBB0_1035

; __device__ __forceinline__ unsigned xb_ld(unsigned* p)              { return __hip_atomic_load(p, __ATOMIC_RELAXED, __HIP_MEMORY_SCOPE_AGENT); }
; __device__ __forceinline__ unsigned xb_add(unsigned* p, unsigned v) { return __hip_atomic_fetch_add(p, v, __ATOMIC_RELAXED, __HIP_MEMORY_SCOPE_AGENT); }
; #define XB_SPIN(cond, bar) do { unsigned _sp = 0; while (cond) { __builtin_amdgcn_s_sleep(1); \
;     if ((++_sp & 255u) == 0u) { if (xb_ld(&(bar)[XB_TMO])) break; if (_sp > XB_SPIN_CAP) { atomicAdd(&(bar)[XB_TMO], 1u); break; } } } } while (0)
; __device__ __forceinline__ void xcd_barrier(const XcdBarrier& b, int tid) {
;     ...
;         const unsigned old = xb_add(&bar[XB_XSUB(bx_)], 1u);
;         const unsigned gen = old / nloc;
;         if (old + 1u == (gen + 1u) * nloc) {
;             __builtin_amdgcn_fence(__ATOMIC_RELEASE, "agent");
;             asm volatile("s_waitcnt vmcnt(0)" ::: "memory");
;             const unsigned og = xb_add(&bar[XB_TOP], 1u);
;             const unsigned tg = og / nx;
;             if (og + 1u == (tg + 1u) * nx) xb_add(&bar[XB_TOPGEN], 1u);
;             else XB_SPIN(xb_ld(&bar[XB_TOPGEN]) == tg, bar);
;             __builtin_amdgcn_fence(__ATOMIC_ACQUIRE, "agent");
;             xb_add(&bar[XB_XGEN(bx_)], 1u);
;             asm volatile("s_waitcnt vmcnt(0)" ::: "memory");
;         } else {
;             XB_SPIN(xb_ld(&bar[XB_XGEN(bx_)]) == gen, bar);
;             __builtin_amdgcn_fence(__ATOMIC_ACQUIRE, "agent");
;             asm volatile("s_waitcnt vmcnt(0)" ::: "memory");
;         }
.LBB0_1101:
	s_lshl_b32 s26, s50, 6
	s_add_i32 s64, s26, 0x500
	s_lshl_b64 s[6:7], s[64:65], 2
	s_add_u32 s6, s58, s6
	s_addc_u32 s7, s59, s7
	v_mov_b64_e32 v[4:5], s[6:7]
	v_mov_b32_e32 v1, 1
	flat_atomic_add v3, v[4:5], v1 sc0
	v_cvt_f32_u32_e32 v1, v2
	v_sub_u32_e32 v4, 0, v2
	v_rcp_iflag_f32_e32 v1, v1
	s_nop 0
	v_mul_f32_e32 v1, 0x4f7ffffe, v1
	v_cvt_u32_f32_e32 v1, v1
	v_mul_lo_u32 v4, v4, v1
	v_mul_hi_u32 v4, v1, v4
	v_add_u32_e32 v1, v1, v4
	s_waitcnt vmcnt(0) lgkmcnt(0)
	v_mul_hi_u32 v1, v3, v1
	v_mul_lo_u32 v4, v1, v2
	v_sub_u32_e32 v4, v3, v4
	v_cmp_ge_u32_e32 vcc, v4, v2
	v_add_u32_e32 v5, 1, v1
	s_nop 0
	v_cndmask_b32_e32 v1, v1, v5, vcc
	v_sub_u32_e32 v5, v4, v2
	v_cndmask_b32_e32 v4, v4, v5, vcc
	v_cmp_ge_u32_e32 vcc, v4, v2
	v_add_u32_e32 v4, 1, v1
	s_nop 0
	v_cndmask_b32_e32 v1, v1, v4, vcc
	v_add_u32_e32 v4, 1, v3
	v_mad_u64_u32 v[2:3], s[6:7], v2, v1, v[2:3]
	v_cmp_ne_u32_e32 vcc, v4, v2
	s_and_saveexec_b64 s[6:7], vcc
	s_xor_b64 s[6:7], exec, s[6:7]
	s_cbranch_execz .LBB0_1114
	s_add_i32 s64, s26, 0x900
	s_lshl_b64 s[8:9], s[64:65], 2
	s_add_u32 s10, s58, 0x3500
	s_addc_u32 s11, s59, 0
	v_mov_b64_e32 v[2:3], s[10:11]
	global_load_dword v0, v[2:3], off sc1
	s_waitcnt vmcnt(0) lgkmcnt(0)
	v_cmp_eq_u32_e32 vcc, v0, v1
	s_and_saveexec_b64 s[8:9], vcc
	s_cbranch_execz .LBB0_1113
	s_mov_b32 s27, 1
	s_mov_b64 s[12:13], 0
	s_branch .LBB0_1105

; __device__ __forceinline__ unsigned xb_ld(unsigned* p)              { return __hip_atomic_load(p, __ATOMIC_RELAXED, __HIP_MEMORY_SCOPE_AGENT); }
; __device__ __forceinline__ unsigned xb_add(unsigned* p, unsigned v) { return __hip_atomic_fetch_add(p, v, __ATOMIC_RELAXED, __HIP_MEMORY_SCOPE_AGENT); }
; #define XB_SPIN(cond, bar) do { unsigned _sp = 0; while (cond) { __builtin_amdgcn_s_sleep(1); \
;     if ((++_sp & 255u) == 0u) { if (xb_ld(&(bar)[XB_TMO])) break; if (_sp > XB_SPIN_CAP) { atomicAdd(&(bar)[XB_TMO], 1u); break; } } } } while (0)
; __device__ __forceinline__ void xcd_barrier(const XcdBarrier& b, int tid) {
;     ...
;         const unsigned old = xb_add(&bar[XB_XSUB(bx_)], 1u);
;         const unsigned gen = old / nloc;
;         if (old + 1u == (gen + 1u) * nloc) {
;             __builtin_amdgcn_fence(__ATOMIC_RELEASE, "agent");
;             asm volatile("s_waitcnt vmcnt(0)" ::: "memory");
;             const unsigned og = xb_add(&bar[XB_TOP], 1u);
;             const unsigned tg = og / nx;
;             if (og + 1u == (tg + 1u) * nx) xb_add(&bar[XB_TOPGEN], 1u);
;             else XB_SPIN(xb_ld(&bar[XB_TOPGEN]) == tg, bar);
;             __builtin_amdgcn_fence(__ATOMIC_ACQUIRE, "agent");
;             xb_add(&bar[XB_XGEN(bx_)], 1u);
;             asm volatile("s_waitcnt vmcnt(0)" ::: "memory");
;         } else {
;             XB_SPIN(xb_ld(&bar[XB_XGEN(bx_)]) == gen, bar);
;             __builtin_amdgcn_fence(__ATOMIC_ACQUIRE, "agent");
;             asm volatile("s_waitcnt vmcnt(0)" ::: "memory");
;         }
.LBB0_1151:
	s_lshl_b32 s28, s50, 6
	s_add_i32 s64, s28, 0x500
	s_lshl_b64 s[6:7], s[64:65], 2
	s_add_u32 s6, s58, s6
	s_addc_u32 s7, s59, s7
	v_mov_b64_e32 v[4:5], s[6:7]
	v_mov_b32_e32 v1, 1
	flat_atomic_add v3, v[4:5], v1 sc0
	v_cvt_f32_u32_e32 v1, v2
	v_sub_u32_e32 v4, 0, v2
	v_rcp_iflag_f32_e32 v1, v1
	s_nop 0
	v_mul_f32_e32 v1, 0x4f7ffffe, v1
	v_cvt_u32_f32_e32 v1, v1
	v_mul_lo_u32 v4, v4, v1
	v_mul_hi_u32 v4, v1, v4
	v_add_u32_e32 v1, v1, v4
	s_waitcnt vmcnt(0) lgkmcnt(0)
	v_mul_hi_u32 v1, v3, v1
	v_mul_lo_u32 v4, v1, v2
	v_sub_u32_e32 v4, v3, v4
	v_cmp_ge_u32_e32 vcc, v4, v2
	v_add_u32_e32 v5, 1, v1
	s_nop 0
	v_cndmask_b32_e32 v1, v1, v5, vcc
	v_sub_u32_e32 v5, v4, v2
	v_cndmask_b32_e32 v4, v4, v5, vcc
	v_cmp_ge_u32_e32 vcc, v4, v2
	v_add_u32_e32 v4, 1, v1
	s_nop 0
	v_cndmask_b32_e32 v1, v1, v4, vcc
	v_add_u32_e32 v4, 1, v3
	v_mad_u64_u32 v[2:3], s[6:7], v2, v1, v[2:3]
	v_cmp_ne_u32_e32 vcc, v4, v2
	s_and_saveexec_b64 s[6:7], vcc
	s_xor_b64 s[6:7], exec, s[6:7]
	s_cbranch_execz .LBB0_1164
	s_add_i32 s64, s28, 0x900
	s_lshl_b64 s[8:9], s[64:65], 2
	s_add_u32 s10, s58, 0x3500
	s_addc_u32 s11, s59, 0
	v_mov_b64_e32 v[2:3], s[10:11]
	global_load_dword v0, v[2:3], off sc1
	s_waitcnt vmcnt(0) lgkmcnt(0)
	v_cmp_eq_u32_e32 vcc, v0, v1
	s_and_saveexec_b64 s[8:9], vcc
	s_cbranch_execz .LBB0_1163
	s_mov_b32 s26, 1
	s_mov_b64 s[12:13], 0
	s_branch .LBB0_1155

; __device__ __forceinline__ unsigned xb_ld(unsigned* p)              { return __hip_atomic_load(p, __ATOMIC_RELAXED, __HIP_MEMORY_SCOPE_AGENT); }
; __device__ __forceinline__ unsigned xb_add(unsigned* p, unsigned v) { return __hip_atomic_fetch_add(p, v, __ATOMIC_RELAXED, __HIP_MEMORY_SCOPE_AGENT); }
; #define XB_SPIN(cond, bar) do { unsigned _sp = 0; while (cond) { __builtin_amdgcn_s_sleep(1); \
;     if ((++_sp & 255u) == 0u) { if (xb_ld(&(bar)[XB_TMO])) break; if (_sp > XB_SPIN_CAP) { atomicAdd(&(bar)[XB_TMO], 1u); break; } } } } while (0)
; __device__ __forceinline__ void xcd_barrier(const XcdBarrier& b, int tid) {
;     ...
;         const unsigned old = xb_add(&bar[XB_XSUB(bx_)], 1u);
;         const unsigned gen = old / nloc;
;         if (old + 1u == (gen + 1u) * nloc) {
;             __builtin_amdgcn_fence(__ATOMIC_RELEASE, "agent");
;             asm volatile("s_waitcnt vmcnt(0)" ::: "memory");
;             const unsigned og = xb_add(&bar[XB_TOP], 1u);
;             const unsigned tg = og / nx;
;             if (og + 1u == (tg + 1u) * nx) xb_add(&bar[XB_TOPGEN], 1u);
;             else XB_SPIN(xb_ld(&bar[XB_TOPGEN]) == tg, bar);
;             __builtin_amdgcn_fence(__ATOMIC_ACQUIRE, "agent");
;             xb_add(&bar[XB_XGEN(bx_)], 1u);
;             asm volatile("s_waitcnt vmcnt(0)" ::: "memory");
;         } else {
;             XB_SPIN(xb_ld(&bar[XB_XGEN(bx_)]) == gen, bar);
;             __builtin_amdgcn_fence(__ATOMIC_ACQUIRE, "agent");
;             asm volatile("s_waitcnt vmcnt(0)" ::: "memory");
;         }
.LBB0_1293:
	s_lshl_b32 s22, s36, 6
	s_add_i32 s64, s22, 0x500
	s_lshl_b64 s[0:1], s[64:65], 2
	s_add_u32 s0, s34, s0
	s_addc_u32 s1, s35, s1
	v_mov_b64_e32 v[4:5], s[0:1]
	v_mov_b32_e32 v1, 1
	flat_atomic_add v3, v[4:5], v1 sc0
	v_cvt_f32_u32_e32 v1, v2
	v_sub_u32_e32 v4, 0, v2
	v_rcp_iflag_f32_e32 v1, v1
	s_nop 0
	v_mul_f32_e32 v1, 0x4f7ffffe, v1
	v_cvt_u32_f32_e32 v1, v1
	v_mul_lo_u32 v4, v4, v1
	v_mul_hi_u32 v4, v1, v4
	v_add_u32_e32 v1, v1, v4
	s_waitcnt vmcnt(0) lgkmcnt(0)
	v_mul_hi_u32 v1, v3, v1
	v_mul_lo_u32 v4, v1, v2
	v_sub_u32_e32 v4, v3, v4
	v_cmp_ge_u32_e32 vcc, v4, v2
	v_add_u32_e32 v5, 1, v1
	s_nop 0
	v_cndmask_b32_e32 v1, v1, v5, vcc
	v_sub_u32_e32 v5, v4, v2
	v_cndmask_b32_e32 v4, v4, v5, vcc
	v_cmp_ge_u32_e32 vcc, v4, v2
	v_add_u32_e32 v4, 1, v1
	s_nop 0
	v_cndmask_b32_e32 v1, v1, v4, vcc
	v_add_u32_e32 v4, 1, v3
	v_mad_u64_u32 v[2:3], s[0:1], v2, v1, v[2:3]
	v_cmp_ne_u32_e32 vcc, v4, v2
	s_and_saveexec_b64 s[0:1], vcc
	s_xor_b64 s[0:1], exec, s[0:1]
	s_cbranch_execz .LBB0_1306
	s_add_i32 s64, s22, 0x900
	s_lshl_b64 s[4:5], s[64:65], 2
	s_add_u32 s6, s34, 0x3500
	s_addc_u32 s7, s35, 0
	v_mov_b64_e32 v[2:3], s[6:7]
	global_load_dword v0, v[2:3], off sc1
	s_waitcnt vmcnt(0) lgkmcnt(0)
	v_cmp_eq_u32_e32 vcc, v0, v1
	s_and_saveexec_b64 s[4:5], vcc
	s_cbranch_execz .LBB0_1305
	s_mov_b32 s23, 1
	s_mov_b64 s[8:9], 0
	s_branch .LBB0_1297
